# speedup vs baseline: 1.0188x; 1.0079x over previous
; #define MFMA(a, b, c) __builtin_amdgcn_mfma_f32_32x32x16_bf16((a), (b), (c), 0, 0, 0)
;     ...
;     while (kt0 < kt_hi) {
;         if (kt1 < kt_hi) asm volatile("s_waitcnt vmcnt(%0)" ::"n"(NI) : "memory");
;         else asm volatile("s_waitcnt vmcnt(0)" ::: "memory");
;         RAW_BARRIER();
;         int kt2 = kt1 + 1;
;         while (kt2 < kt_hi && pol.bskip(kt2)) ++kt2;
;         if (kt2 < kt_hi) issue(kt2, b >= 1 ? b - 1 : 2);
;         const char* sK = smem + b * STAGE;
;         const char* sV = sK + KBYTES;
;         const int kt = kt0;
;         const int mode = pol.wmode(kt);
;         if (mode) {
;             auto qk = [&](const int sub, f32x16 (&st)[QS]) {
; #pragma unroll
;                 for (int qs = 0; qs < QS; ++qs) zero_acc(st[qs]);
; #pragma unroll
;                 for (int s = 0; s < DQK / 16; ++s) {
;                     bf16x8 kf;
;                     if (DQK == 64) kf = *(const bf16x8*)(sK + sub * 4096 + (klane ^ (s << 5)));
;                     else kf = *(const bf16x8*)(sK + sub * 6144 + klane + s * 32 + (s == 4 ? wrap4 : s == 5 ? wrap5 : 0));
; #pragma unroll
;                     for (int qs = 0; qs < QS; ++qs) st[qs] = MFMA(kf, qf[qs][s], st[qs]);
;                 }
;             };
;             auto sm_pv = [&](const int sub, f32x16 (&st)[QS]) {
; #pragma unroll
;                 for (int qs = 0; qs < QS; ++qs) {
;                     bool exact = true;
;                     if ((QS == 1 || DQK == 96 || Pol::FASTEXP) && mode == 1 && __all(seen[qs] && (m[qs] == 0.f))) {
;                         float ps = 0.f;
; #pragma unroll
;                         for (int r = 0; r < 16; ++r) {
;                             const float pv = __builtin_amdgcn_exp2f(st[qs][r]);
;                             st[qs][r] = pv;
;                             ps += pv;
;                         }
;                         if (!__any(!(ps < 1048576.f))) {
;                             l[qs] += ps;
;                             exact = false;
;                         } else {
;                             asm volatile("" ::: "memory");
;                             zero_acc(st[qs]);
; #pragma unroll
;                             for (int s = 0; s < DQK / 16; ++s) {
;                                 bf16x8 kf;
;                                 if (DQK == 64) kf = *(const bf16x8*)(sK + sub * 4096 + (klane ^ (s << 5)));
.LBB0_1166:
	v_add_u32_e32 v15, s63, v179
	s_waitcnt vmcnt(10)
	ds_read_b128 v[2:5], v15
	v_add_u32_e32 v189, v15, v184
	ds_read_b128 v[226:229], v189 offset:160
	v_add_u32_e32 v188, v15, v183
	s_add_i32 s0, s8, 0xffffffbf
	v_cmp_gt_i32_e64 s[16:17], s0, v173
	v_cmp_le_i32_e64 s[0:1], s0, v173
	s_mov_b64 s[44:45], s[16:17]
	s_waitcnt lgkmcnt(0)
	v_mfma_f32_32x32x16_bf16 v[96:111], v[2:5], v[112:115], 0
	v_mfma_f32_32x32x16_bf16 v[80:95], v[2:5], v[136:139], 0
	ds_read_b128 v[2:5], v15 offset:32
	ds_read_b128 v[238:241], v15 offset:64
	ds_read_b128 v[234:237], v15 offset:96
	s_waitcnt lgkmcnt(2)
	v_mfma_f32_32x32x16_bf16 v[96:111], v[2:5], v[116:119], v[96:111]
	v_mfma_f32_32x32x16_bf16 v[80:95], v[2:5], v[140:143], v[80:95]
	ds_read_b128 v[2:5], v188 offset:128
	s_waitcnt lgkmcnt(2)
	v_mfma_f32_32x32x16_bf16 v[96:111], v[238:241], v[120:123], v[96:111]
	v_mfma_f32_32x32x16_bf16 v[80:95], v[238:241], v[144:147], v[80:95]
	s_waitcnt lgkmcnt(1)
	v_mfma_f32_32x32x16_bf16 v[96:111], v[234:237], v[124:127], v[96:111]
	v_mfma_f32_32x32x16_bf16 v[80:95], v[234:237], v[148:151], v[80:95]
	s_waitcnt lgkmcnt(0)
	v_mfma_f32_32x32x16_bf16 v[96:111], v[2:5], v[128:131], v[96:111]
	v_mfma_f32_32x32x16_bf16 v[80:95], v[2:5], v[152:155], v[80:95]
	v_mfma_f32_32x32x16_bf16 v[96:111], v[226:229], v[132:135], v[96:111]
	v_mfma_f32_32x32x16_bf16 v[80:95], v[226:229], v[156:159], v[80:95]
	s_and_saveexec_b64 s[36:37], s[0:1]
	s_cbranch_execz .LBB0_1173
	v_cmp_eq_f32_e32 vcc, 0, v0
	s_and_b64 s[18:19], s[10:11], vcc
	v_cndmask_b32_e64 v2, 0, 1, s[18:19]
	v_cmp_ne_u32_e32 vcc, 0, v2
	s_cmp_eq_u64 vcc, exec
	s_mov_b64 s[38:39], -1
	s_cbranch_scc0 .LBB0_1170
	s_nop 1
	v_exp_f32_e32 v2, v96
	v_exp_f32_e32 v3, v97
	v_exp_f32_e32 v4, v98
	v_exp_f32_e32 v5, v99
	v_add_f32_e32 v6, 0, v2
	v_add_f32_e32 v6, v3, v6
	v_add_f32_e32 v6, v4, v6
	v_add_f32_e32 v10, v5, v6
	v_exp_f32_e32 v6, v100
	v_exp_f32_e32 v7, v101
	v_exp_f32_e32 v8, v102
	v_exp_f32_e32 v9, v103
	v_add_f32_e32 v10, v6, v10
	v_add_f32_e32 v10, v7, v10
	v_add_f32_e32 v10, v8, v10
	v_add_f32_e32 v96, v9, v10
	v_exp_f32_e32 v10, v104
	v_exp_f32_e32 v11, v105
	v_exp_f32_e32 v12, v106
	v_exp_f32_e32 v13, v107
	v_add_f32_e32 v96, v10, v96
	v_exp_f32_e32 v191, v108
	v_add_f32_e32 v96, v11, v96
	v_exp_f32_e32 v193, v109
	v_add_f32_e32 v96, v12, v96
	v_exp_f32_e32 v194, v110
	v_add_f32_e32 v96, v13, v96
	v_exp_f32_e32 v195, v111
	v_add_f32_e32 v96, v191, v96
	v_add_f32_e32 v96, v193, v96
	v_add_f32_e32 v96, v194, v96
	v_add_f32_e32 v192, v195, v96
	v_cmp_ngt_f32_e32 vcc, s25, v192
	s_cbranch_vccz .LBB0_1171
	ds_read_b128 v[96:99], v15
	ds_read_b128 v[226:229], v15 offset:32
	s_waitcnt lgkmcnt(1)
	v_mfma_f32_32x32x16_bf16 v[96:111], v[96:99], v[112:115], 0
	s_waitcnt lgkmcnt(0)
	v_mfma_f32_32x32x16_bf16 v[96:111], v[226:229], v[116:119], v[96:111]
	ds_read_b128 v[226:229], v15 offset:64
	s_waitcnt lgkmcnt(0)
	v_mfma_f32_32x32x16_bf16 v[96:111], v[226:229], v[120:123], v[96:111]
	ds_read_b128 v[226:229], v15 offset:96
	s_waitcnt lgkmcnt(0)
	v_mfma_f32_32x32x16_bf16 v[96:111], v[226:229], v[124:127], v[96:111]
	ds_read_b128 v[226:229], v188 offset:128
	s_waitcnt lgkmcnt(0)
	v_mfma_f32_32x32x16_bf16 v[96:111], v[226:229], v[128:131], v[96:111]
	ds_read_b128 v[226:229], v189 offset:160
	s_waitcnt lgkmcnt(0)
	v_mfma_f32_32x32x16_bf16 v[96:111], v[226:229], v[132:135], v[96:111]
	s_branch .LBB0_1172

; #define MFMA(a, b, c) __builtin_amdgcn_mfma_f32_32x32x16_bf16((a), (b), (c), 0, 0, 0)
;     ...
;     while (kt0 < kt_hi) {
;         if (kt1 < kt_hi) asm volatile("s_waitcnt vmcnt(%0)" ::"n"(NI) : "memory");
;         else asm volatile("s_waitcnt vmcnt(0)" ::: "memory");
;         RAW_BARRIER();
;         int kt2 = kt1 + 1;
;         while (kt2 < kt_hi && pol.bskip(kt2)) ++kt2;
;         if (kt2 < kt_hi) issue(kt2, b >= 1 ? b - 1 : 2);
;         const char* sK = smem + b * STAGE;
;         const char* sV = sK + KBYTES;
;         const int kt = kt0;
;         const int mode = pol.wmode(kt);
;         if (mode) {
;             auto qk = [&](const int sub, f32x16 (&st)[QS]) {
; #pragma unroll
;                 for (int qs = 0; qs < QS; ++qs) zero_acc(st[qs]);
; #pragma unroll
;                 for (int s = 0; s < DQK / 16; ++s) {
;                     bf16x8 kf;
;                     if (DQK == 64) kf = *(const bf16x8*)(sK + sub * 4096 + (klane ^ (s << 5)));
;                     else kf = *(const bf16x8*)(sK + sub * 6144 + klane + s * 32 + (s == 4 ? wrap4 : s == 5 ? wrap5 : 0));
; #pragma unroll
;                     for (int qs = 0; qs < QS; ++qs) st[qs] = MFMA(kf, qf[qs][s], st[qs]);
;                 }
;             };
;             auto sm_pv = [&](const int sub, f32x16 (&st)[QS]) {
; #pragma unroll
;                 for (int qs = 0; qs < QS; ++qs) {
;                     bool exact = true;
;                     if ((QS == 1 || DQK == 96 || Pol::FASTEXP) && mode == 1 && __all(seen[qs] && (m[qs] == 0.f))) {
;                         float ps = 0.f;
; #pragma unroll
;                         for (int r = 0; r < 16; ++r) {
;                             const float pv = __builtin_amdgcn_exp2f(st[qs][r]);
;                             st[qs][r] = pv;
;                             ps += pv;
;                         }
;                         if (!__any(!(ps < 1048576.f))) {
;                             l[qs] += ps;
;                             exact = false;
;                         } else {
;                             asm volatile("" ::: "memory");
;                             zero_acc(st[qs]);
; #pragma unroll
;                             for (int s = 0; s < DQK / 16; ++s) {
;                                 bf16x8 kf;
;                                 if (DQK == 64) kf = *(const bf16x8*)(sK + sub * 4096 + (klane ^ (s << 5)));
.LBB0_1289:
	v_add_u32_e32 v155, s20, v147
	s_waitcnt vmcnt(8)
	ds_read_b128 v[66:69], v155
	v_add_u32_e32 v156, s20, v148
	ds_read_b128 v[158:161], v156
	v_add_u32_e32 v152, s20, v149
	v_add_u32_e32 v153, s20, v150
	v_cmp_eq_f32_e32 vcc, 0, v151
	s_and_b64 s[18:19], s[38:39], vcc
	s_mov_b64 s[44:45], -1
	s_waitcnt lgkmcnt(0)
	v_mfma_f32_32x32x16_bf16 v[82:97], v[66:69], v[98:101], 0
	v_mfma_f32_32x32x16_bf16 v[66:81], v[66:69], v[114:117], 0
	v_mfma_f32_32x32x16_bf16 v[82:97], v[158:161], v[102:105], v[82:97]
	v_mfma_f32_32x32x16_bf16 v[66:81], v[158:161], v[118:121], v[66:81]
	ds_read_b128 v[158:161], v152
	s_waitcnt lgkmcnt(0)
	v_mfma_f32_32x32x16_bf16 v[82:97], v[158:161], v[106:109], v[82:97]
	v_mfma_f32_32x32x16_bf16 v[66:81], v[158:161], v[122:125], v[66:81]
	ds_read_b128 v[158:161], v153
	s_waitcnt lgkmcnt(0)
	v_mfma_f32_32x32x16_bf16 v[82:97], v[158:161], v[110:113], v[82:97]
	v_mfma_f32_32x32x16_bf16 v[66:81], v[158:161], v[126:129], v[66:81]
	v_cndmask_b32_e64 v158, 0, 1, s[18:19]
	v_cmp_ne_u32_e32 vcc, 0, v158
	s_cmp_lg_u64 vcc, exec
	s_cbranch_scc1 .LBB0_1292
	s_nop 6
	v_exp_f32_e32 v159, v82
	v_exp_f32_e32 v160, v83
	v_exp_f32_e32 v161, v84
	v_exp_f32_e32 v163, v85
	v_add_f32_e32 v82, 0, v159
	v_exp_f32_e32 v166, v86
	v_add_f32_e32 v82, v160, v82
	v_exp_f32_e32 v167, v87
	v_add_f32_e32 v82, v161, v82
	v_exp_f32_e32 v169, v88
	v_add_f32_e32 v82, v163, v82
	v_exp_f32_e32 v171, v89
	v_add_f32_e32 v82, v166, v82
	v_exp_f32_e32 v162, v90
	v_add_f32_e32 v82, v167, v82
	v_exp_f32_e32 v164, v91
	v_add_f32_e32 v82, v169, v82
	v_exp_f32_e32 v165, v92
	v_add_f32_e32 v82, v171, v82
	v_exp_f32_e32 v168, v93
	v_add_f32_e32 v82, v162, v82
	v_exp_f32_e32 v170, v94
	v_add_f32_e32 v82, v164, v82
	v_exp_f32_e32 v172, v95
	v_add_f32_e32 v82, v165, v82
	v_exp_f32_e32 v173, v96
	v_add_f32_e32 v82, v168, v82
	v_exp_f32_e32 v174, v97
	v_add_f32_e32 v82, v170, v82
	v_add_f32_e32 v82, v172, v82
	v_add_f32_e32 v82, v173, v82
	v_add_f32_e32 v158, v174, v82
	v_cmp_ngt_f32_e32 vcc, s25, v158
	s_cbranch_vccz .LBB0_1308
	ds_read_b128 v[82:85], v155
	ds_read_b128 v[176:179], v156
	s_waitcnt lgkmcnt(1)
	v_mfma_f32_32x32x16_bf16 v[82:97], v[82:85], v[98:101], 0
	s_waitcnt lgkmcnt(0)
	v_mfma_f32_32x32x16_bf16 v[82:97], v[176:179], v[102:105], v[82:97]
	ds_read_b128 v[176:179], v152
	s_waitcnt lgkmcnt(0)
	v_mfma_f32_32x32x16_bf16 v[82:97], v[176:179], v[106:109], v[82:97]
	ds_read_b128 v[176:179], v153
	s_waitcnt lgkmcnt(0)
	v_mfma_f32_32x32x16_bf16 v[82:97], v[176:179], v[110:113], v[82:97]

; #define MFMA(a, b, c) __builtin_amdgcn_mfma_f32_32x32x16_bf16((a), (b), (c), 0, 0, 0)
;     ...
;     while (kt0 < kt_hi) {
;         if (kt1 < kt_hi) asm volatile("s_waitcnt vmcnt(%0)" ::"n"(NI) : "memory");
;         else asm volatile("s_waitcnt vmcnt(0)" ::: "memory");
;         RAW_BARRIER();
;         int kt2 = kt1 + 1;
;         while (kt2 < kt_hi && pol.bskip(kt2)) ++kt2;
;         if (kt2 < kt_hi) issue(kt2, b >= 1 ? b - 1 : 2);
;         const char* sK = smem + b * STAGE;
;         const char* sV = sK + KBYTES;
;         const int kt = kt0;
;         const int mode = pol.wmode(kt);
;         if (mode) {
;             auto qk = [&](const int sub, f32x16 (&st)[QS]) {
; #pragma unroll
;                 for (int qs = 0; qs < QS; ++qs) zero_acc(st[qs]);
; #pragma unroll
;                 for (int s = 0; s < DQK / 16; ++s) {
;                     bf16x8 kf;
;                     if (DQK == 64) kf = *(const bf16x8*)(sK + sub * 4096 + (klane ^ (s << 5)));
;                     else kf = *(const bf16x8*)(sK + sub * 6144 + klane + s * 32 + (s == 4 ? wrap4 : s == 5 ? wrap5 : 0));
; #pragma unroll
;                     for (int qs = 0; qs < QS; ++qs) st[qs] = MFMA(kf, qf[qs][s], st[qs]);
;                 }
;             };
;             auto sm_pv = [&](const int sub, f32x16 (&st)[QS]) {
; #pragma unroll
;                 for (int qs = 0; qs < QS; ++qs) {
;                     bool exact = true;
;                     if ((QS == 1 || DQK == 96 || Pol::FASTEXP) && mode == 1 && __all(seen[qs] && (m[qs] == 0.f))) {
;                         float ps = 0.f;
; #pragma unroll
;                         for (int r = 0; r < 16; ++r) {
;                             const float pv = __builtin_amdgcn_exp2f(st[qs][r]);
;                             st[qs][r] = pv;
;                             ps += pv;
;                         }
;                         if (!__any(!(ps < 1048576.f))) {
;                             l[qs] += ps;
;                             exact = false;
;                         } else {
;                             asm volatile("" ::: "memory");
;                             zero_acc(st[qs]);
; #pragma unroll
;                             for (int s = 0; s < DQK / 16; ++s) {
;                                 bf16x8 kf;
;                                 if (DQK == 64) kf = *(const bf16x8*)(sK + sub * 4096 + (klane ^ (s << 5)));
.LBB0_1368:
	s_andn2_b64 s[0:1], s[12:13], exec
	s_and_b64 s[12:13], s[16:17], exec
	v_cmp_le_i32_e32 vcc, s63, v168
	s_or_b64 s[12:13], s[0:1], s[12:13]
	s_and_saveexec_b64 s[38:39], vcc
	s_cbranch_execz .LBB0_1412
	v_add_u32_e32 v4, s19, v173
	s_waitcnt vmcnt(12)
	ds_read_b128 v[6:9], v4
	v_add_u32_e32 v5, s19, v172
	v_add_u32_e32 v3, s19, v170
	v_add_u32_e32 v2, s19, v169
	s_add_i32 s0, s63, 63
	v_cmp_gt_i32_e64 s[42:43], s0, v168
	v_cmp_le_i32_e64 s[0:1], s0, v168
	s_mov_b64 s[56:57], s[42:43]
	s_waitcnt lgkmcnt(0)
	v_mfma_f32_32x32x16_bf16 v[96:111], v[6:9], v[132:135], 0
	ds_read_b128 v[186:189], v5
	ds_read_b128 v[182:185], v3
	ds_read_b128 v[6:9], v2
	ds_read_b128 v[190:193], v4 offset:4096
	s_waitcnt lgkmcnt(3)
	v_mfma_f32_32x32x16_bf16 v[96:111], v[186:189], v[128:131], v[96:111]
	ds_read_b128 v[186:189], v5 offset:4096
	s_waitcnt lgkmcnt(3)
	v_mfma_f32_32x32x16_bf16 v[96:111], v[182:185], v[136:139], v[96:111]
	ds_read_b128 v[182:185], v3 offset:4096
	s_waitcnt lgkmcnt(3)
	v_mfma_f32_32x32x16_bf16 v[96:111], v[6:9], v[140:143], v[96:111]
	ds_read_b128 v[6:9], v2 offset:4096
	s_waitcnt lgkmcnt(3)
	v_mfma_f32_32x32x16_bf16 v[80:95], v[190:193], v[132:135], 0
	s_waitcnt lgkmcnt(2)
	v_mfma_f32_32x32x16_bf16 v[80:95], v[186:189], v[128:131], v[80:95]
	s_waitcnt lgkmcnt(1)
	v_mfma_f32_32x32x16_bf16 v[80:95], v[182:185], v[136:139], v[80:95]
	s_waitcnt lgkmcnt(0)
	v_mfma_f32_32x32x16_bf16 v[80:95], v[6:9], v[140:143], v[80:95]
	s_and_saveexec_b64 s[36:37], s[0:1]
	s_cbranch_execz .LBB0_1376
	v_cmp_eq_f32_e32 vcc, 0, v174
	s_and_b64 s[18:19], s[16:17], vcc
	v_cndmask_b32_e64 v6, 0, 1, s[18:19]
	v_cmp_ne_u32_e32 vcc, 0, v6
	s_cmp_eq_u64 vcc, exec
	s_mov_b64 s[44:45], -1
	s_cbranch_scc0 .LBB0_1373
	v_exp_f32_e32 v112, v96
	v_exp_f32_e32 v113, v97
	v_exp_f32_e32 v114, v98
	v_exp_f32_e32 v115, v99
	v_add_f32_e32 v6, 0, v112
	v_exp_f32_e32 v116, v100
	v_add_f32_e32 v6, v113, v6
	v_exp_f32_e32 v117, v101
	v_add_f32_e32 v6, v114, v6
	v_exp_f32_e32 v118, v102
	v_add_f32_e32 v6, v115, v6
	v_exp_f32_e32 v119, v103
	v_add_f32_e32 v6, v116, v6
	v_exp_f32_e32 v120, v104
	v_add_f32_e32 v6, v117, v6
	v_exp_f32_e32 v121, v105
	v_add_f32_e32 v6, v118, v6
	v_exp_f32_e32 v122, v106
	v_add_f32_e32 v6, v119, v6
	v_exp_f32_e32 v123, v107
	v_add_f32_e32 v6, v120, v6
	v_exp_f32_e32 v124, v108
	v_add_f32_e32 v6, v121, v6
	v_exp_f32_e32 v125, v109
	v_add_f32_e32 v6, v122, v6
	v_exp_f32_e32 v126, v110
	v_add_f32_e32 v6, v123, v6
	v_exp_f32_e32 v127, v111
	v_add_f32_e32 v6, v124, v6
	v_add_f32_e32 v6, v125, v6
	v_add_f32_e32 v6, v126, v6
	v_add_f32_e32 v6, v127, v6
	v_cmp_ngt_f32_e32 vcc, s25, v6
	s_cbranch_vccz .LBB0_1374
	ds_read_b128 v[190:193], v4
	ds_read_b128 v[186:189], v5
	ds_read_b128 v[182:185], v3
	ds_read_b128 v[8:11], v2
	s_waitcnt lgkmcnt(3)
	v_mfma_f32_32x32x16_bf16 v[96:111], v[190:193], v[132:135], 0
	s_waitcnt lgkmcnt(2)
	v_mfma_f32_32x32x16_bf16 v[96:111], v[186:189], v[128:131], v[96:111]
	s_waitcnt lgkmcnt(1)
	v_mfma_f32_32x32x16_bf16 v[96:111], v[182:185], v[136:139], v[96:111]
	s_waitcnt lgkmcnt(0)
	v_mfma_f32_32x32x16_bf16 v[96:111], v[8:11], v[140:143], v[96:111]
	s_branch .LBB0_1375
